# P + de-serialised EpiResid residual loads and EpiScale row-stat loads (hoisted, one wait)
# speedup vs baseline: 1.0018x; 1.0002x over previous
; __device__ __forceinline__ float row_rs(const float* ssq, int row, int fq) {
;     const f32x4 a = *(const f32x4*)(ssq + (size_t)row * 32 + fq * 8), b = *(const f32x4*)(ssq + (size_t)row * 32 + fq * 8 + 4);
;     float s = ((a[0] + a[1]) + (a[2] + a[3])) + ((b[0] + b[1]) + (b[2] + b[3]));
;     s += __shfl_xor(s, 16); s += __shfl_xor(s, 32);
;     return __builtin_amdgcn_rsqf(s * (1.0f / 2048.0f) + 1e-6f);
; }
;     __device__ __forceinline__ void operator()(const f32x4 (&acc)[2][2][4][2], const Unit& u, int wr, int wc, int fr, int fq) const {
;     ...
; #pragma unroll
;         for (int ai = 0; ai < 2; ++ai)
; #pragma unroll
;             for (int m = 0; m < 4; ++m) { const int row = row0 + ai * HALF + m * 16; const float rs = ssq ? row_rs(ssq, row, fq) : 1.0f;
.Lpeel_exit_165:
	s_andn2_b64 vcc, exec, s[36:37]
	s_cbranch_vccnz .Lp3_pre_skip
	v_lshl_add_u32 v184, s54, 8, v145
	v_cmp_lt_i32_e32 vcc, v179, v180
	v_lshlrev_b32_e32 v184, 7, v184
	v_mov_b32_e32 v185, 0
	v_cndmask_b32_e32 v182, v178, v179, vcc
	v_cmp_lt_i32_e32 vcc, v187, v180
	v_lshl_add_u64 v[184:185], v[184:185], 0, v[134:135]
	v_mov_b32_e32 v154, 0x1000
	v_cndmask_b32_e32 v183, v178, v187, vcc
	v_mov_b32_e32 v155, 0
	v_lshlrev_b32_e32 v182, 2, v182
	v_lshlrev_b32_e32 v183, 2, v183
	global_load_dwordx4 v[164:167], v[184:185], off
	global_load_dwordx4 v[168:171], v[184:185], off offset:16
	global_load_dwordx4 v[172:175], v[184:185], off offset:2048
	global_load_dwordx4 v[188:191], v[184:185], off offset:2064
	v_lshl_add_u64 v[184:185], v[184:185], 0, v[154:155]
	v_mov_b32_e32 v154, 0x3000
	global_load_dwordx4 v[192:195], v[184:185], off
	global_load_dwordx4 v[196:199], v[184:185], off offset:16
	global_load_dwordx4 v[200:203], v[184:185], off offset:2048
	global_load_dwordx4 v[204:207], v[184:185], off offset:2064
	v_lshl_add_u64 v[184:185], v[184:185], 0, v[154:155]
	v_mov_b32_e32 v154, 0x1000
	global_load_dwordx4 v[208:211], v[184:185], off
	global_load_dwordx4 v[212:215], v[184:185], off offset:16
	global_load_dwordx4 v[216:219], v[184:185], off offset:2048
	global_load_dwordx4 v[220:223], v[184:185], off offset:2064
	v_lshl_add_u64 v[184:185], v[184:185], 0, v[154:155]
	global_load_dwordx4 v[224:227], v[184:185], off
	global_load_dwordx4 v[228:231], v[184:185], off offset:16
	global_load_dwordx4 v[232:235], v[184:185], off offset:2048
	global_load_dwordx4 v[248:251], v[184:185], off offset:2064

;     __device__ __forceinline__ void operator()(const f32x4 (&acc)[2][2][4][2], const Unit& u, int wr, int wc, int fr, int fq) const {
;     ...
;             for (int m = 0; m < 4; ++m) { const int row = row0 + ai * HALF + m * 16; float q = 0.f;
; #pragma unroll
;                 for (int bj = 0; bj < 2; ++bj) { const size_t off = (size_t)row * 2048 + col0 + bj * HALF;
;                     f32x4 b0, b1;
;                     if (base32) { b0 = *(const f32x4*)(base32 + off); b1 = *(const f32x4*)(base32 + off + 4); }
;                     else { const u32x4 bw = *(const u32x4*)(xb + off);
;                         b0 = (f32x4){__uint_as_float(bw.x << 16), __uint_as_float(bw.x & 0xffff0000u), __uint_as_float(bw.y << 16), __uint_as_float(bw.y & 0xffff0000u)};
;                         b1 = (f32x4){__uint_as_float(bw.z << 16), __uint_as_float(bw.z & 0xffff0000u), __uint_as_float(bw.w << 16), __uint_as_float(bw.w & 0xffff0000u)}; }
.Lpeel_exit_218:
	v_lshl_add_u32 v188, s26, 8, v148
	v_lshl_or_b32 v190, s17, 8, v150
	v_mov_b32_e32 v189, 0
	v_mov_b32_e32 v191, 0
	v_lshlrev_b64 v[182:183], 11, v[188:189]
	v_mov_b32_e32 v184, 0x10000
	v_lshl_add_u64 v[182:183], v[182:183], 0, v[190:191]
	v_mov_b32_e32 v185, 0
	v_lshl_add_u64 v[182:183], v[182:183], 1, s[12:13]
	global_load_dwordx4 v[164:167], v[182:183], off
	global_load_dwordx4 v[168:171], v[182:183], off offset:256
	v_lshl_add_u64 v[182:183], v[182:183], 0, v[184:185]
	global_load_dwordx4 v[172:175], v[182:183], off
	global_load_dwordx4 v[192:195], v[182:183], off offset:256
	v_lshl_add_u64 v[182:183], v[182:183], 0, v[184:185]
	global_load_dwordx4 v[196:199], v[182:183], off
	global_load_dwordx4 v[200:203], v[182:183], off offset:256
	v_lshl_add_u64 v[182:183], v[182:183], 0, v[184:185]
	global_load_dwordx4 v[204:207], v[182:183], off
	global_load_dwordx4 v[208:211], v[182:183], off offset:256
	v_mov_b32_e32 v184, 0x50000
	s_nop 0
	v_lshl_add_u64 v[182:183], v[182:183], 0, v[184:185]
	v_mov_b32_e32 v184, 0x10000
	global_load_dwordx4 v[212:215], v[182:183], off
	global_load_dwordx4 v[216:219], v[182:183], off offset:256
	v_lshl_add_u64 v[182:183], v[182:183], 0, v[184:185]
	global_load_dwordx4 v[220:223], v[182:183], off
	global_load_dwordx4 v[224:227], v[182:183], off offset:256
	v_lshl_add_u64 v[182:183], v[182:183], 0, v[184:185]
	global_load_dwordx4 v[228:231], v[182:183], off
	global_load_dwordx4 v[232:235], v[182:183], off offset:256
	v_lshl_add_u64 v[182:183], v[182:183], 0, v[184:185]
	global_load_dwordx4 v[240:243], v[182:183], off
	global_load_dwordx4 v[244:247], v[182:183], off offset:256
	s_and_b64 vcc, exec, s[36:37]
	s_cbranch_vccz .LBB0_221
	s_barrier
